# late weight conversion spread over the idle second GEMM rounds of phases 7/8/9 (was all in phase 7)
# speedup vs baseline: 1.0305x; 1.0048x over previous
.LBB0_1473:
	s_or_b64 exec, exec, s[6:7]
	s_cmp_gt_i32 s48, 32
	s_movk_i32 s99, 0x127f
	s_cselect_b32 s99, 0x1ff, s99
	s_mov_b32 s98, 0
.Ltr_late_entry:
	v_and_b32_e32 v33, 63, v178
	s_mov_b32 s0, s99
	v_cmp_lt_i32_e32 vcc, s0, v92
	v_lshrrev_b32_e32 v50, 5, v33
	v_and_b32_e32 v34, 31, v178
	s_and_saveexec_b64 s[0:1], vcc
	s_xor_b64 s[4:5], exec, s[0:1]
	v_lshrrev_b32_e32 v50, 5, v33
	v_and_b32_e32 v34, 31, v178
	v_mov_b32_e32 v35, 0
	s_or_saveexec_b64 s[4:5], s[4:5]
	v_mov_b32_e32 v2, 0
	v_add_u32_e32 v139, 0x1b10, v92
	v_mov_b32_e32 v1, v2
	v_mov_b32_e32 v4, v2
	v_mov_b32_e32 v3, v2
	v_mov_b32_e32 v6, v2
	v_mov_b32_e32 v5, v2
	v_mov_b32_e32 v8, v2
	v_mov_b32_e32 v7, v2
	v_mov_b32_e32 v10, v2
	v_mov_b32_e32 v9, v2
	v_mov_b32_e32 v12, v2
	v_mov_b32_e32 v11, v2
	v_mov_b32_e32 v14, v2
	v_mov_b32_e32 v13, v2
	v_mov_b32_e32 v16, v2
	v_mov_b32_e32 v15, v2
	v_mov_b32_e32 v18, v2
	v_mov_b32_e32 v17, v2
	v_mov_b32_e32 v20, v2
	v_mov_b32_e32 v19, v2
	v_mov_b32_e32 v22, v2
	v_mov_b32_e32 v21, v2
	v_mov_b32_e32 v24, v2
	v_mov_b32_e32 v23, v2
	v_mov_b32_e32 v26, v2
	v_mov_b32_e32 v25, v2
	v_mov_b32_e32 v28, v2
	v_mov_b32_e32 v27, v2
	v_mov_b32_e32 v30, v2
	v_mov_b32_e32 v29, v2
	v_mov_b32_e32 v32, v2
	v_mov_b32_e32 v31, v2
	s_xor_b64 exec, exec, s[4:5]
	s_cbranch_execz .LBB0_1561
	s_movk_i32 s0, 0x1aaf
	v_cmp_lt_u32_e32 vcc, s0, v139
	s_and_saveexec_b64 s[0:1], vcc
	s_xor_b64 s[6:7], exec, s[0:1]
	s_cbranch_execz .LBB0_1494
	s_movk_i32 s0, 0x1acf
	v_cmp_lt_u32_e32 vcc, s0, v139
	s_and_saveexec_b64 s[0:1], vcc
	s_xor_b64 s[12:13], exec, s[0:1]
	s_cbranch_execz .LBB0_1491
	s_movk_i32 s0, 0xe4f0
	v_cmp_gt_u32_e32 vcc, s0, v92
	s_and_saveexec_b64 s[0:1], vcc
	s_xor_b64 s[14:15], exec, s[0:1]
	s_cbranch_execz .LBB0_1488
	s_movk_i32 s0, 0x1d0f
	v_cmp_lt_u32_e32 vcc, s0, v139
	s_and_saveexec_b64 s[0:1], vcc
	s_xor_b64 s[16:17], exec, s[0:1]
	s_cbranch_execz .LBB0_1485
	s_movk_i32 s0, 0x280f
	v_cmp_lt_u32_e32 vcc, s0, v139
	s_and_saveexec_b64 s[0:1], vcc
	s_xor_b64 s[18:19], exec, s[0:1]
	s_cbranch_execz .LBB0_1482
	s_add_i32 s0, 0, 0x20108
	v_mov_b32_e32 v1, s0
	ds_read_b64 v[2:3], v1
	v_add_u32_e32 v4, 0xfffff300, v92
	v_lshlrev_b32_e32 v1, 1, v4
	v_and_b32_e32 v1, 0x7fffffc0, v1
	s_waitcnt lgkmcnt(0)
	v_readfirstlane_b32 s20, v2
	v_lshlrev_b32_e32 v2, 5, v4
	v_readfirstlane_b32 s21, v3
	v_and_b32_e32 v36, 0x3e0, v2

.LBB0_1561:
	s_or_b64 exec, exec, s[4:5]
	s_sub_i32 s0, s48, s3
	s_lshl_b32 s3, s0, 3
	s_add_u32 s12, s46, 0x2900000
	s_addc_u32 s13, s47, 0
	s_add_u32 s14, s46, 0x1e00000
	s_addc_u32 s15, s47, 0
	s_add_u32 s16, s46, 0x1c00000
	s_addc_u32 s17, s47, 0
	v_lshlrev_b32_e32 v36, 8, v178
	s_add_u32 s18, s46, 0x2e80000
	v_and_b32_e32 v36, 0x3c000, v36
	s_addc_u32 s19, s47, 0
	v_add_u32_e32 v38, 0, v36
	v_mul_i32_i24_e32 v36, 0x84, v50
	v_lshlrev_b32_e32 v37, 2, v34
	v_lshrrev_b32_e32 v61, 3, v33
	v_lshlrev_b32_e32 v33, 3, v178
	s_add_u32 s20, s46, 0x1a00000
	v_add3_u32 v37, v38, v36, v37
	v_and_b32_e32 v36, 56, v33
	s_addc_u32 s21, s47, 0
	v_mul_u32_u24_e32 v33, 0x84, v36
	v_lshlrev_b32_e32 v40, 2, v61
	s_add_u32 s22, s46, 0x100000
	v_mov_b32_e32 v39, 0
	v_add3_u32 v62, v38, v33, v40
	v_or_b32_e32 v63, 8, v61
	v_or_b32_e32 v64, 16, v61
	v_or_b32_e32 v65, 24, v61
	s_addc_u32 s23, s47, 0
	s_mov_b64 s[24:25], 0
	s_add_i32 s62, s99, 0x1b11
	s_add_i32 s63, s99, 0x1b10
	s_movk_i32 s64, 0x148f
	s_movk_i32 s65, 0x188f
	s_movk_i32 s66, 0x1a8f
	s_movk_i32 s67, 0x1aaf
	s_movk_i32 s68, 0x1acf
	s_movk_i32 s69, 0x1b0f
	s_movk_i32 s70, 0x1d0f
	s_movk_i32 s71, 0x280f
	s_add_i32 s72, 0, 0x20108
	s_add_i32 s73, 0, 0x200e8
	s_add_i32 s74, 0, 0x200e0
	s_add_i32 s75, 0, 0x200a8
	s_add_i32 s76, 0, 0x200a0
	s_add_i32 s77, 0, 0x20090
	s_add_i32 s78, 0, 0x200d8
	s_add_i32 s79, 0, 0x20078
	s_mov_b32 s80, 0x18e6527b
	s_movk_i32 s81, 0x149
	s_add_i32 s82, 0, 0x20038
	s_movk_i32 s83, 0xa0
	v_mov_b32_e32 v68, 0xfffcaa00
	v_mov_b32_e32 v69, 0xfffcae00
	v_mov_b32_e32 v70, 0x2900
	s_branch .LBB0_1565

.LBB0_1827:
	s_or_b64 exec, exec, s[24:25]
	s_cmp_eq_u32 s98, 8
	s_cbranch_scc1 .Ltr_ret8
	s_cmp_eq_u32 s98, 9
	s_cbranch_scc1 .Ltr_ret9

.LBB0_1914:
	s_waitcnt vmcnt(0)
	s_barrier
	s_cmp_gt_i32 s48, 32
	s_cbranch_scc0 .Ltr_skip8
	s_cmp_lt_u32 s2, 16
	s_cbranch_scc1 .Ltr_skip8
	s_sub_i32 s0, s2, 16
	v_lshl_add_u32 v92, s0, 3, v179
	v_add_u32_e32 v92, 0x200, v92
	s_movk_i32 s99, 0xcff
	s_mov_b32 s3, 16
	s_mov_b32 s98, 8
	s_branch .Ltr_late_entry
.Ltr_ret8:
	v_bfe_u32 v1, v178, 2, 4
.Ltr_skip8:
.LBB0_1915:
	s_cmp_gt_i32 s51, 9
	s_cselect_b64 s[4:5], -1, 0
	s_and_b64 s[0:1], s[8:9], s[4:5]
	s_andn2_b64 vcc, exec, s[0:1]
	s_cbranch_vccnz .LBB0_1983
	s_cmp_gt_i32 s50, -1
	s_mov_b64 s[6:7], -1
	s_cbranch_scc0 .LBB0_1970
	s_waitcnt vmcnt(0)
	s_barrier
	s_and_saveexec_b64 s[6:7], s[84:85]
	s_cbranch_execz .LBB0_1969
	s_add_i32 s0, 0, 0x20800
	v_mov_b32_e32 v2, s0
	s_waitcnt vmcnt(0) expcnt(0) lgkmcnt(0)
	ds_read_b32 v4, v2
	s_add_i32 s0, 0, 0x20804
	v_mov_b32_e32 v2, s0
	ds_read_b32 v2, v2
	s_waitcnt lgkmcnt(1)
	v_cmp_ne_u32_e32 vcc, 0, v4
	s_cbranch_vccnz .LBB0_1933
	s_add_u32 s8, s46, 0x80200
	s_addc_u32 s9, s47, 0
	s_add_u32 s10, s46, 0x80400
	s_addc_u32 s11, s47, 0
	s_add_u32 s12, s46, 0x80500
	s_addc_u32 s13, s47, 0
	s_add_u32 s14, s46, 0x80600
	s_addc_u32 s15, s47, 0
	s_add_u32 s16, s46, 0x80700
	s_addc_u32 s17, s47, 0
	s_add_u32 s18, s46, 0x80800
	s_addc_u32 s19, s47, 0
	s_add_u32 s20, s46, 0x80900
	s_addc_u32 s21, s47, 0
	s_add_u32 s22, s46, 0x80a00
	s_addc_u32 s23, s47, 0
	s_add_u32 s24, s46, 0x80b00
	s_addc_u32 s25, s47, 0
	s_add_u32 s26, s46, 0x80c00
	s_addc_u32 s27, s47, 0
	s_add_u32 s28, s46, 0x80d00
	s_addc_u32 s29, s47, 0
	s_add_u32 s30, s46, 0x80e00
	s_addc_u32 s31, s47, 0
	s_add_u32 s34, s46, 0x80f00
	s_addc_u32 s35, s47, 0
	s_add_u32 s36, s46, 0x81000
	s_addc_u32 s37, s47, 0
	s_add_u32 s38, s46, 0x81100
	s_addc_u32 s39, s47, 0
	s_add_u32 s40, s46, 0x81200
	v_readlane_b32 s0, v249, 0
	s_addc_u32 s41, s47, 0
	s_mul_i32 s0, s49, s0
	s_add_u32 s42, s46, 0x81300
	s_mul_i32 s0, s0, s48
	s_addc_u32 s43, s47, 0
	s_mov_b32 s1, 1
	v_mov_b32_e32 v18, 0
	s_branch .LBB0_1921

.LBB0_2017:
	s_waitcnt vmcnt(0)
	s_barrier
	s_cmp_gt_i32 s48, 32
	s_cbranch_scc0 .Ltr_skip9
	s_cmp_lt_u32 s2, 16
	s_cbranch_scc1 .Ltr_skip9
	s_sub_i32 s0, s2, 16
	v_lshl_add_u32 v92, s0, 3, v179
	v_add_u32_e32 v92, 0xd00, v92
	s_movk_i32 s99, 0x127f
	s_mov_b32 s3, 16
	s_mov_b32 s98, 9
	s_branch .Ltr_late_entry

.Ltr_skip9:
.LBB0_2018:
	s_cmp_gt_i32 s51, 10
	s_cselect_b64 s[4:5], -1, 0
	s_and_b64 s[0:1], s[8:9], s[4:5]
	s_andn2_b64 vcc, exec, s[0:1]
	s_cbranch_vccnz .LBB0_2086
	s_cmp_gt_i32 s50, -1
	s_mov_b64 s[6:7], -1
	s_cbranch_scc0 .LBB0_2073
	s_waitcnt vmcnt(0)
	s_waitcnt lgkmcnt(0)
	s_barrier
	s_and_saveexec_b64 s[6:7], s[84:85]
	s_cbranch_execz .LBB0_2072
	s_add_i32 s0, 0, 0x20800
	v_mov_b32_e32 v2, s0
	s_waitcnt vmcnt(0) expcnt(0) lgkmcnt(0)
	ds_read_b32 v4, v2
	s_add_i32 s0, 0, 0x20804
	v_mov_b32_e32 v2, s0
	ds_read_b32 v2, v2
	s_waitcnt lgkmcnt(1)
	v_cmp_ne_u32_e32 vcc, 0, v4
	s_cbranch_vccnz .LBB0_2036
	s_add_u32 s8, s46, 0x80200
	s_addc_u32 s9, s47, 0
	s_add_u32 s10, s46, 0x80400
	s_addc_u32 s11, s47, 0
	s_add_u32 s12, s46, 0x80500
	s_addc_u32 s13, s47, 0
	s_add_u32 s14, s46, 0x80600
	s_addc_u32 s15, s47, 0
	s_add_u32 s16, s46, 0x80700
	s_addc_u32 s17, s47, 0
	s_add_u32 s18, s46, 0x80800
	s_addc_u32 s19, s47, 0
	s_add_u32 s20, s46, 0x80900
	s_addc_u32 s21, s47, 0
	s_add_u32 s22, s46, 0x80a00
	s_addc_u32 s23, s47, 0
	s_add_u32 s24, s46, 0x80b00
	s_addc_u32 s25, s47, 0
	s_add_u32 s26, s46, 0x80c00
	s_addc_u32 s27, s47, 0
	s_add_u32 s28, s46, 0x80d00
	s_addc_u32 s29, s47, 0
	s_add_u32 s30, s46, 0x80e00
	s_addc_u32 s31, s47, 0
	s_add_u32 s34, s46, 0x80f00
	s_addc_u32 s35, s47, 0
	s_add_u32 s36, s46, 0x81000
	s_addc_u32 s37, s47, 0
	s_add_u32 s38, s46, 0x81100
	s_addc_u32 s39, s47, 0
	s_add_u32 s40, s46, 0x81200
	v_readlane_b32 s0, v249, 0
	s_addc_u32 s41, s47, 0
	s_mul_i32 s0, s49, s0
	s_add_u32 s42, s46, 0x81300
	s_mul_i32 s0, s0, s48
	s_addc_u32 s43, s47, 0
	s_mov_b32 s1, 1
	v_mov_b32_e32 v18, 0
	s_branch .LBB0_2024
